# residual/gate loads of wout,w2 epilogues requested in the tile's last half-step; compute-dtype comment
# speedup vs baseline: 1.0728x; 1.0025x over previous
.Lg128_w2_next_retry:
	s_cmp_ge_u32 s12, 128
	s_cbranch_scc1 .Lg128_w2_nonext
	s_lshr_b32 s3, s12, 6
	s_lshl_b32 s3, s3, 3
	s_add_u32 s3, s3, s65
	s_mov_b32 s17, s3
	s_mov_b32 s3, 0
	s_lshl_b32 s17, s17, 3
	s_bfe_u32 s23, s12, 0x30003
	s_add_u32 s13, s17, s23
	s_lshl_b32 s3, s3, 3
	s_and_b32 s23, s12, 7
	s_add_u32 s14, s3, s23
	s_lshl_b32 s13, s13, 7
	s_lshl_b32 s14, s14, 7
	s_lshl_b32 s3, s15, 5
	s_add_u32 s17, s3, s13
	s_mul_i32 s17, s17, 0x2000
	s_add_u32 s6, s18, s17
	s_addc_u32 s7, s19, 0
	s_add_u32 s17, s3, s14
	s_mul_i32 s17, s17, 0x2000
	s_add_u32 s8, s20, s17
	s_addc_u32 s9, s21, 0
	v_mov_b32_e32 v176, v177
	s_mov_b32 s16, 1
	s_waitcnt lgkmcnt(0)
	v_mfma_f32_16x16x32_bf16 v[2:5], v[90:93], v[106:109], v[2:5]
	ds_read_b128 v[144:147], v142 offset:1024
	v_mfma_f32_16x16x32_bf16 v[6:9], v[94:97], v[106:109], v[6:9]
	ds_read_b128 v[148:151], v142 offset:3072
	v_mfma_f32_16x16x32_bf16 v[10:13], v[98:101], v[106:109], v[10:13]
	ds_read_b128 v[152:155], v142 offset:5120
	v_mfma_f32_16x16x32_bf16 v[14:17], v[102:105], v[106:109], v[14:17]
	ds_read_b128 v[156:159], v142 offset:7168
	v_mfma_f32_16x16x32_bf16 v[18:21], v[90:93], v[110:113], v[18:21]
	ds_read_b128 v[160:163], v141 offset:1024
	v_mfma_f32_16x16x32_bf16 v[22:25], v[94:97], v[110:113], v[22:25]
	ds_read_b128 v[164:167], v141 offset:3072
	v_mfma_f32_16x16x32_bf16 v[26:29], v[98:101], v[110:113], v[26:29]
	ds_read_b128 v[168:171], v141 offset:5120
	v_mfma_f32_16x16x32_bf16 v[30:33], v[102:105], v[110:113], v[30:33]
	ds_read_b128 v[172:175], v141 offset:7168
	v_mfma_f32_16x16x32_bf16 v[34:37], v[90:93], v[114:117], v[34:37]
	v_mfma_f32_16x16x32_bf16 v[38:41], v[94:97], v[114:117], v[38:41]
	v_mfma_f32_16x16x32_bf16 v[42:45], v[98:101], v[114:117], v[42:45]
	v_mfma_f32_16x16x32_bf16 v[46:49], v[102:105], v[114:117], v[46:49]
	v_mfma_f32_16x16x32_bf16 v[50:53], v[90:93], v[118:121], v[50:53]
	v_mfma_f32_16x16x32_bf16 v[54:57], v[94:97], v[118:121], v[54:57]
	v_mfma_f32_16x16x32_bf16 v[58:61], v[98:101], v[118:121], v[58:61]
	v_mfma_f32_16x16x32_bf16 v[62:65], v[102:105], v[118:121], v[62:65]
	s_waitcnt vmcnt(0) lgkmcnt(0)
	s_barrier
	v_mfma_f32_16x16x32_bf16 v[2:5], v[144:147], v[160:163], v[2:5]
	ds_read_b128 v[90:93], v142 offset:32768
	s_add_u32 m0, s22, 0x0
	v_mov_b32_e32 v179, v176
	global_load_lds_dwordx4 v179, s[6:7]
	v_mfma_f32_16x16x32_bf16 v[6:9], v[148:151], v[160:163], v[6:9]
	ds_read_b128 v[94:97], v142 offset:34816
	s_add_u32 m0, s22, 0x400
	v_add_u32_e32 v180, 0x40, v176
	global_load_lds_dwordx4 v180, s[6:7]
	v_mfma_f32_16x16x32_bf16 v[10:13], v[152:155], v[160:163], v[10:13]
	ds_read_b128 v[98:101], v142 offset:36864
	s_add_u32 m0, s22, 0x800
	v_add_u32_e32 v179, 0x20000, v176
	global_load_lds_dwordx4 v179, s[6:7]
	v_mfma_f32_16x16x32_bf16 v[14:17], v[156:159], v[160:163], v[14:17]
	ds_read_b128 v[102:105], v142 offset:38912
	s_add_u32 m0, s22, 0xc00
	v_add_u32_e32 v180, 0x20040, v176
	global_load_lds_dwordx4 v180, s[6:7]
	v_mfma_f32_16x16x32_bf16 v[18:21], v[144:147], v[164:167], v[18:21]
	ds_read_b128 v[106:109], v141 offset:32768
	s_add_u32 m0, s22, 0x4000
	v_mov_b32_e32 v179, v176
	global_load_lds_dwordx4 v179, s[8:9]
	v_mfma_f32_16x16x32_bf16 v[22:25], v[148:151], v[164:167], v[22:25]
	ds_read_b128 v[110:113], v141 offset:34816
	s_add_u32 m0, s22, 0x4400
	v_add_u32_e32 v180, 0x40, v176
	global_load_lds_dwordx4 v180, s[8:9]
	v_mfma_f32_16x16x32_bf16 v[26:29], v[152:155], v[164:167], v[26:29]
	ds_read_b128 v[114:117], v141 offset:36864
	s_add_u32 m0, s22, 0x4800
	v_add_u32_e32 v179, 0x20000, v176
	global_load_lds_dwordx4 v179, s[8:9]
	v_mfma_f32_16x16x32_bf16 v[30:33], v[156:159], v[164:167], v[30:33]
	ds_read_b128 v[118:121], v141 offset:38912
	s_add_u32 m0, s22, 0x4c00
	v_add_u32_e32 v180, 0x20040, v176
	global_load_lds_dwordx4 v180, s[8:9]
	v_mfma_f32_16x16x32_bf16 v[34:37], v[144:147], v[168:171], v[34:37]
	v_mfma_f32_16x16x32_bf16 v[38:41], v[148:151], v[168:171], v[38:41]
	v_mfma_f32_16x16x32_bf16 v[42:45], v[152:155], v[168:171], v[42:45]
	v_mfma_f32_16x16x32_bf16 v[46:49], v[156:159], v[168:171], v[46:49]
	v_mfma_f32_16x16x32_bf16 v[50:53], v[144:147], v[172:175], v[50:53]
	v_mfma_f32_16x16x32_bf16 v[54:57], v[148:151], v[172:175], v[54:57]
	v_mfma_f32_16x16x32_bf16 v[58:61], v[152:155], v[172:175], v[58:61]
	v_mfma_f32_16x16x32_bf16 v[62:65], v[156:159], v[172:175], v[62:65]
	v_add_u32_e32 v176, 0x80, v176
	s_waitcnt lgkmcnt(0)
	v_mfma_f32_16x16x32_bf16 v[2:5], v[90:93], v[106:109], v[2:5]
	ds_read_b128 v[144:147], v142 offset:33792
	v_mfma_f32_16x16x32_bf16 v[6:9], v[94:97], v[106:109], v[6:9]
	ds_read_b128 v[148:151], v142 offset:35840
	v_mfma_f32_16x16x32_bf16 v[10:13], v[98:101], v[106:109], v[10:13]
	ds_read_b128 v[152:155], v142 offset:37888
	v_mfma_f32_16x16x32_bf16 v[14:17], v[102:105], v[106:109], v[14:17]
	ds_read_b128 v[156:159], v142 offset:39936
	v_mfma_f32_16x16x32_bf16 v[18:21], v[90:93], v[110:113], v[18:21]
	ds_read_b128 v[160:163], v141 offset:33792
	v_mfma_f32_16x16x32_bf16 v[22:25], v[94:97], v[110:113], v[22:25]
	ds_read_b128 v[164:167], v141 offset:35840
	v_mfma_f32_16x16x32_bf16 v[26:29], v[98:101], v[110:113], v[26:29]
	ds_read_b128 v[168:171], v141 offset:37888
	v_mfma_f32_16x16x32_bf16 v[30:33], v[102:105], v[110:113], v[30:33]
	ds_read_b128 v[172:175], v141 offset:39936
	v_mfma_f32_16x16x32_bf16 v[34:37], v[90:93], v[114:117], v[34:37]
	v_mfma_f32_16x16x32_bf16 v[38:41], v[94:97], v[114:117], v[38:41]
	v_mfma_f32_16x16x32_bf16 v[42:45], v[98:101], v[114:117], v[42:45]
	v_mfma_f32_16x16x32_bf16 v[46:49], v[102:105], v[114:117], v[46:49]
	v_mfma_f32_16x16x32_bf16 v[50:53], v[90:93], v[118:121], v[50:53]
	v_mfma_f32_16x16x32_bf16 v[54:57], v[94:97], v[118:121], v[54:57]
	v_mfma_f32_16x16x32_bf16 v[58:61], v[98:101], v[118:121], v[58:61]
	v_mfma_f32_16x16x32_bf16 v[62:65], v[102:105], v[118:121], v[62:65]
	s_waitcnt vmcnt(0) lgkmcnt(0)
	s_barrier
	v_mfma_f32_16x16x32_bf16 v[2:5], v[144:147], v[160:163], v[2:5]
	ds_read_b128 v[90:93], v142
	s_add_u32 m0, s22, 0x8000
	v_mov_b32_e32 v179, v176
	global_load_lds_dwordx4 v179, s[6:7]
	v_mfma_f32_16x16x32_bf16 v[6:9], v[148:151], v[160:163], v[6:9]
	ds_read_b128 v[94:97], v142 offset:2048
	s_add_u32 m0, s22, 0x8400
	v_add_u32_e32 v180, 0x40, v176
	global_load_lds_dwordx4 v180, s[6:7]
	v_mfma_f32_16x16x32_bf16 v[10:13], v[152:155], v[160:163], v[10:13]
	ds_read_b128 v[98:101], v142 offset:4096
	s_add_u32 m0, s22, 0x8800
	v_add_u32_e32 v179, 0x20000, v176
	global_load_lds_dwordx4 v179, s[6:7]
	v_mfma_f32_16x16x32_bf16 v[14:17], v[156:159], v[160:163], v[14:17]
	ds_read_b128 v[102:105], v142 offset:6144
	s_add_u32 m0, s22, 0x8c00
	v_add_u32_e32 v180, 0x20040, v176
	global_load_lds_dwordx4 v180, s[6:7]
	v_mfma_f32_16x16x32_bf16 v[18:21], v[144:147], v[164:167], v[18:21]
	ds_read_b128 v[106:109], v141
	s_add_u32 m0, s22, 0xc000
	v_mov_b32_e32 v179, v176
	global_load_lds_dwordx4 v179, s[8:9]
	v_mfma_f32_16x16x32_bf16 v[22:25], v[148:151], v[164:167], v[22:25]
	ds_read_b128 v[110:113], v141 offset:2048
	s_add_u32 m0, s22, 0xc400
	v_add_u32_e32 v180, 0x40, v176
	global_load_lds_dwordx4 v180, s[8:9]
	v_mfma_f32_16x16x32_bf16 v[26:29], v[152:155], v[164:167], v[26:29]
	ds_read_b128 v[114:117], v141 offset:4096
	s_add_u32 m0, s22, 0xc800
	v_add_u32_e32 v179, 0x20000, v176
	global_load_lds_dwordx4 v179, s[8:9]
	v_mfma_f32_16x16x32_bf16 v[30:33], v[156:159], v[164:167], v[30:33]
	ds_read_b128 v[118:121], v141 offset:6144
	s_add_u32 m0, s22, 0xcc00
	v_add_u32_e32 v180, 0x20040, v176
	global_load_lds_dwordx4 v180, s[8:9]
	v_mfma_f32_16x16x32_bf16 v[34:37], v[144:147], v[168:171], v[34:37]
	global_load_dwordx4 v[196:199], v181, s[4:5]
	v_mfma_f32_16x16x32_bf16 v[38:41], v[148:151], v[168:171], v[38:41]
	global_load_dwordx4 v[200:203], v181, s[4:5] offset:64
	global_load_dwordx4 v[204:207], v181, s[4:5] offset:128
	v_mfma_f32_16x16x32_bf16 v[42:45], v[152:155], v[168:171], v[42:45]
	global_load_dwordx4 v[212:215], v181, s[4:5] offset:192
	v_mfma_f32_16x16x32_bf16 v[46:49], v[156:159], v[168:171], v[46:49]
	global_load_dwordx4 v[66:69], v178, s[26:27]
	global_load_dwordx4 v[70:73], v178, s[26:27] offset:64
	v_mfma_f32_16x16x32_bf16 v[50:53], v[144:147], v[172:175], v[50:53]
	global_load_dwordx4 v[74:77], v178, s[26:27] offset:128
	v_mfma_f32_16x16x32_bf16 v[54:57], v[148:151], v[172:175], v[54:57]
	global_load_dwordx4 v[78:81], v178, s[26:27] offset:192
	v_add_u32_e32 v216, 0x10000, v178
	global_load_dwordx4 v[82:85], v216, s[26:27]
	v_mfma_f32_16x16x32_bf16 v[58:61], v[152:155], v[172:175], v[58:61]
	global_load_dwordx4 v[86:89], v216, s[26:27] offset:64
	v_mfma_f32_16x16x32_bf16 v[62:65], v[156:159], v[172:175], v[62:65]
	global_load_dwordx4 v[122:125], v216, s[26:27] offset:128
	global_load_dwordx4 v[126:129], v216, s[26:27] offset:192
	v_add_u32_e32 v176, 0x80, v176
	s_branch .Lg128_w2_epi
.Lg128_w2_nonext:
	s_mov_b32 s16, 0
	s_waitcnt lgkmcnt(0)
	v_mfma_f32_16x16x32_bf16 v[2:5], v[90:93], v[106:109], v[2:5]
	ds_read_b128 v[144:147], v142 offset:1024
	v_mfma_f32_16x16x32_bf16 v[6:9], v[94:97], v[106:109], v[6:9]
	ds_read_b128 v[148:151], v142 offset:3072
	v_mfma_f32_16x16x32_bf16 v[10:13], v[98:101], v[106:109], v[10:13]
	ds_read_b128 v[152:155], v142 offset:5120
	v_mfma_f32_16x16x32_bf16 v[14:17], v[102:105], v[106:109], v[14:17]
	ds_read_b128 v[156:159], v142 offset:7168
	v_mfma_f32_16x16x32_bf16 v[18:21], v[90:93], v[110:113], v[18:21]
	ds_read_b128 v[160:163], v141 offset:1024
	v_mfma_f32_16x16x32_bf16 v[22:25], v[94:97], v[110:113], v[22:25]
	ds_read_b128 v[164:167], v141 offset:3072
	v_mfma_f32_16x16x32_bf16 v[26:29], v[98:101], v[110:113], v[26:29]
	ds_read_b128 v[168:171], v141 offset:5120
	v_mfma_f32_16x16x32_bf16 v[30:33], v[102:105], v[110:113], v[30:33]
	ds_read_b128 v[172:175], v141 offset:7168
	v_mfma_f32_16x16x32_bf16 v[34:37], v[90:93], v[114:117], v[34:37]
	v_mfma_f32_16x16x32_bf16 v[38:41], v[94:97], v[114:117], v[38:41]
	v_mfma_f32_16x16x32_bf16 v[42:45], v[98:101], v[114:117], v[42:45]
	v_mfma_f32_16x16x32_bf16 v[46:49], v[102:105], v[114:117], v[46:49]
	v_mfma_f32_16x16x32_bf16 v[50:53], v[90:93], v[118:121], v[50:53]
	v_mfma_f32_16x16x32_bf16 v[54:57], v[94:97], v[118:121], v[54:57]
	v_mfma_f32_16x16x32_bf16 v[58:61], v[98:101], v[118:121], v[58:61]
	v_mfma_f32_16x16x32_bf16 v[62:65], v[102:105], v[118:121], v[62:65]
	s_waitcnt vmcnt(0) lgkmcnt(0)
	s_barrier
	v_mfma_f32_16x16x32_bf16 v[2:5], v[144:147], v[160:163], v[2:5]
	ds_read_b128 v[90:93], v142 offset:32768
	v_mfma_f32_16x16x32_bf16 v[6:9], v[148:151], v[160:163], v[6:9]
	ds_read_b128 v[94:97], v142 offset:34816
	v_mfma_f32_16x16x32_bf16 v[10:13], v[152:155], v[160:163], v[10:13]
	ds_read_b128 v[98:101], v142 offset:36864
	v_mfma_f32_16x16x32_bf16 v[14:17], v[156:159], v[160:163], v[14:17]
	ds_read_b128 v[102:105], v142 offset:38912
	v_mfma_f32_16x16x32_bf16 v[18:21], v[144:147], v[164:167], v[18:21]
	ds_read_b128 v[106:109], v141 offset:32768
	v_mfma_f32_16x16x32_bf16 v[22:25], v[148:151], v[164:167], v[22:25]
	ds_read_b128 v[110:113], v141 offset:34816
	v_mfma_f32_16x16x32_bf16 v[26:29], v[152:155], v[164:167], v[26:29]
	ds_read_b128 v[114:117], v141 offset:36864
	v_mfma_f32_16x16x32_bf16 v[30:33], v[156:159], v[164:167], v[30:33]
	ds_read_b128 v[118:121], v141 offset:38912
	v_mfma_f32_16x16x32_bf16 v[34:37], v[144:147], v[168:171], v[34:37]
	v_mfma_f32_16x16x32_bf16 v[38:41], v[148:151], v[168:171], v[38:41]
	v_mfma_f32_16x16x32_bf16 v[42:45], v[152:155], v[168:171], v[42:45]
	v_mfma_f32_16x16x32_bf16 v[46:49], v[156:159], v[168:171], v[46:49]
	v_mfma_f32_16x16x32_bf16 v[50:53], v[144:147], v[172:175], v[50:53]
	v_mfma_f32_16x16x32_bf16 v[54:57], v[148:151], v[172:175], v[54:57]
	v_mfma_f32_16x16x32_bf16 v[58:61], v[152:155], v[172:175], v[58:61]
	v_mfma_f32_16x16x32_bf16 v[62:65], v[156:159], v[172:175], v[62:65]
	s_waitcnt lgkmcnt(0)
	v_mfma_f32_16x16x32_bf16 v[2:5], v[90:93], v[106:109], v[2:5]
	ds_read_b128 v[144:147], v142 offset:33792
	v_mfma_f32_16x16x32_bf16 v[6:9], v[94:97], v[106:109], v[6:9]
	ds_read_b128 v[148:151], v142 offset:35840
	v_mfma_f32_16x16x32_bf16 v[10:13], v[98:101], v[106:109], v[10:13]
	ds_read_b128 v[152:155], v142 offset:37888
	v_mfma_f32_16x16x32_bf16 v[14:17], v[102:105], v[106:109], v[14:17]
	ds_read_b128 v[156:159], v142 offset:39936
	v_mfma_f32_16x16x32_bf16 v[18:21], v[90:93], v[110:113], v[18:21]
	ds_read_b128 v[160:163], v141 offset:33792
	v_mfma_f32_16x16x32_bf16 v[22:25], v[94:97], v[110:113], v[22:25]
	ds_read_b128 v[164:167], v141 offset:35840
	v_mfma_f32_16x16x32_bf16 v[26:29], v[98:101], v[110:113], v[26:29]
	ds_read_b128 v[168:171], v141 offset:37888
	v_mfma_f32_16x16x32_bf16 v[30:33], v[102:105], v[110:113], v[30:33]
	ds_read_b128 v[172:175], v141 offset:39936
	v_mfma_f32_16x16x32_bf16 v[34:37], v[90:93], v[114:117], v[34:37]
	v_mfma_f32_16x16x32_bf16 v[38:41], v[94:97], v[114:117], v[38:41]
	v_mfma_f32_16x16x32_bf16 v[42:45], v[98:101], v[114:117], v[42:45]
	v_mfma_f32_16x16x32_bf16 v[46:49], v[102:105], v[114:117], v[46:49]
	v_mfma_f32_16x16x32_bf16 v[50:53], v[90:93], v[118:121], v[50:53]
	v_mfma_f32_16x16x32_bf16 v[54:57], v[94:97], v[118:121], v[54:57]
	v_mfma_f32_16x16x32_bf16 v[58:61], v[98:101], v[118:121], v[58:61]
	v_mfma_f32_16x16x32_bf16 v[62:65], v[102:105], v[118:121], v[62:65]
	s_waitcnt vmcnt(0) lgkmcnt(0)
	s_barrier
	v_mfma_f32_16x16x32_bf16 v[2:5], v[144:147], v[160:163], v[2:5]
	v_mfma_f32_16x16x32_bf16 v[6:9], v[148:151], v[160:163], v[6:9]
	v_mfma_f32_16x16x32_bf16 v[10:13], v[152:155], v[160:163], v[10:13]
	v_mfma_f32_16x16x32_bf16 v[14:17], v[156:159], v[160:163], v[14:17]
	v_mfma_f32_16x16x32_bf16 v[18:21], v[144:147], v[164:167], v[18:21]
	v_mfma_f32_16x16x32_bf16 v[22:25], v[148:151], v[164:167], v[22:25]
	v_mfma_f32_16x16x32_bf16 v[26:29], v[152:155], v[164:167], v[26:29]
	v_mfma_f32_16x16x32_bf16 v[30:33], v[156:159], v[164:167], v[30:33]
	v_mfma_f32_16x16x32_bf16 v[34:37], v[144:147], v[168:171], v[34:37]
	global_load_dwordx4 v[196:199], v181, s[4:5]
	v_mfma_f32_16x16x32_bf16 v[38:41], v[148:151], v[168:171], v[38:41]
	global_load_dwordx4 v[200:203], v181, s[4:5] offset:64
	global_load_dwordx4 v[204:207], v181, s[4:5] offset:128
	v_mfma_f32_16x16x32_bf16 v[42:45], v[152:155], v[168:171], v[42:45]
	global_load_dwordx4 v[212:215], v181, s[4:5] offset:192
	v_mfma_f32_16x16x32_bf16 v[46:49], v[156:159], v[168:171], v[46:49]
	global_load_dwordx4 v[66:69], v178, s[26:27]
	global_load_dwordx4 v[70:73], v178, s[26:27] offset:64
	v_mfma_f32_16x16x32_bf16 v[50:53], v[144:147], v[172:175], v[50:53]
	global_load_dwordx4 v[74:77], v178, s[26:27] offset:128
	v_mfma_f32_16x16x32_bf16 v[54:57], v[148:151], v[172:175], v[54:57]
	global_load_dwordx4 v[78:81], v178, s[26:27] offset:192
	v_add_u32_e32 v216, 0x10000, v178
	global_load_dwordx4 v[82:85], v216, s[26:27]
	v_mfma_f32_16x16x32_bf16 v[58:61], v[152:155], v[172:175], v[58:61]
	global_load_dwordx4 v[86:89], v216, s[26:27] offset:64
	v_mfma_f32_16x16x32_bf16 v[62:65], v[156:159], v[172:175], v[62:65]
	global_load_dwordx4 v[122:125], v216, s[26:27] offset:128
	global_load_dwordx4 v[126:129], v216, s[26:27] offset:192
.Lg128_w2_epi:
	s_waitcnt vmcnt(0)
	v_pk_fma_f32 v[2:3], v[196:197], v[2:3], v[66:67]
	v_pk_fma_f32 v[4:5], v[198:199], v[4:5], v[68:69]
	v_pk_fma_f32 v[6:7], v[200:201], v[6:7], v[70:71]
	v_pk_fma_f32 v[8:9], v[202:203], v[8:9], v[72:73]
	v_pk_fma_f32 v[10:11], v[204:205], v[10:11], v[74:75]
	v_pk_fma_f32 v[12:13], v[206:207], v[12:13], v[76:77]
	v_pk_fma_f32 v[14:15], v[212:213], v[14:15], v[78:79]
	v_pk_fma_f32 v[16:17], v[214:215], v[16:17], v[80:81]
	v_pk_fma_f32 v[18:19], v[196:197], v[18:19], v[82:83]
	v_pk_fma_f32 v[20:21], v[198:199], v[20:21], v[84:85]
	v_pk_fma_f32 v[22:23], v[200:201], v[22:23], v[86:87]
	v_pk_fma_f32 v[24:25], v[202:203], v[24:25], v[88:89]
	v_pk_fma_f32 v[26:27], v[204:205], v[26:27], v[122:123]
	v_pk_fma_f32 v[28:29], v[206:207], v[28:29], v[124:125]
	v_pk_fma_f32 v[30:31], v[212:213], v[30:31], v[126:127]
	v_pk_fma_f32 v[32:33], v[214:215], v[32:33], v[128:129]
	v_add_u32_e32 v179, 0x20000, v178
	global_load_dwordx4 v[66:69], v179, s[26:27]
	global_load_dwordx4 v[70:73], v179, s[26:27] offset:64
	global_load_dwordx4 v[74:77], v179, s[26:27] offset:128
	global_load_dwordx4 v[78:81], v179, s[26:27] offset:192
	v_add_u32_e32 v180, 0x30000, v178
	global_load_dwordx4 v[82:85], v180, s[26:27]
	global_load_dwordx4 v[86:89], v180, s[26:27] offset:64
	global_load_dwordx4 v[122:125], v180, s[26:27] offset:128
	global_load_dwordx4 v[126:129], v180, s[26:27] offset:192
	global_store_dwordx4 v178, v[2:5], s[10:11]
	global_store_dwordx4 v178, v[6:9], s[10:11] offset:64
	global_store_dwordx4 v178, v[10:13], s[10:11] offset:128
	global_store_dwordx4 v178, v[14:17], s[10:11] offset:192
	v_add_u32_e32 v180, 0x10000, v178
	global_store_dwordx4 v180, v[18:21], s[10:11]
	global_store_dwordx4 v180, v[22:25], s[10:11] offset:64
	global_store_dwordx4 v180, v[26:29], s[10:11] offset:128
	global_store_dwordx4 v180, v[30:33], s[10:11] offset:192
	s_waitcnt vmcnt(8)
	v_pk_fma_f32 v[34:35], v[196:197], v[34:35], v[66:67]
	v_pk_fma_f32 v[36:37], v[198:199], v[36:37], v[68:69]
	v_pk_fma_f32 v[38:39], v[200:201], v[38:39], v[70:71]
	v_pk_fma_f32 v[40:41], v[202:203], v[40:41], v[72:73]
	v_pk_fma_f32 v[42:43], v[204:205], v[42:43], v[74:75]
	v_pk_fma_f32 v[44:45], v[206:207], v[44:45], v[76:77]
	v_pk_fma_f32 v[46:47], v[212:213], v[46:47], v[78:79]
	v_pk_fma_f32 v[48:49], v[214:215], v[48:49], v[80:81]
	v_pk_fma_f32 v[50:51], v[196:197], v[50:51], v[82:83]
	v_pk_fma_f32 v[52:53], v[198:199], v[52:53], v[84:85]
	v_pk_fma_f32 v[54:55], v[200:201], v[54:55], v[86:87]
	v_pk_fma_f32 v[56:57], v[202:203], v[56:57], v[88:89]
	v_pk_fma_f32 v[58:59], v[204:205], v[58:59], v[122:123]
	v_pk_fma_f32 v[60:61], v[206:207], v[60:61], v[124:125]
	v_pk_fma_f32 v[62:63], v[212:213], v[62:63], v[126:127]
	v_pk_fma_f32 v[64:65], v[214:215], v[64:65], v[128:129]
	v_add_u32_e32 v179, 0x20000, v178
	global_store_dwordx4 v179, v[34:37], s[10:11]
	global_store_dwordx4 v179, v[38:41], s[10:11] offset:64
	global_store_dwordx4 v179, v[42:45], s[10:11] offset:128
	global_store_dwordx4 v179, v[46:49], s[10:11] offset:192
	v_add_u32_e32 v180, 0x30000, v178
	global_store_dwordx4 v180, v[50:53], s[10:11]
	global_store_dwordx4 v180, v[54:57], s[10:11] offset:64
	global_store_dwordx4 v180, v[58:61], s[10:11] offset:128
	global_store_dwordx4 v180, v[62:65], s[10:11] offset:192
	s_cmp_lg_u32 s16, 0
	s_cbranch_scc1 .Lg128_w2_tile

.Lg128_wo_next_retry:
	s_cmp_ge_u32 s12, 128
	s_cbranch_scc1 .Lg128_wo_nonext
	s_lshr_b32 s3, s12, 6
	s_lshl_b32 s3, s3, 3
	s_add_u32 s3, s3, s65
	s_mov_b32 s17, s3
	s_mov_b32 s3, 0
	s_lshl_b32 s17, s17, 3
	s_bfe_u32 s23, s12, 0x30003
	s_add_u32 s13, s17, s23
	s_lshl_b32 s3, s3, 3
	s_and_b32 s23, s12, 7
	s_add_u32 s14, s3, s23
	s_lshl_b32 s13, s13, 7
	s_lshl_b32 s14, s14, 7
	s_lshl_b32 s3, s15, 5
	s_add_u32 s17, s3, s13
	s_mul_i32 s17, s17, 0x800
	s_add_u32 s6, s18, s17
	s_addc_u32 s7, s19, 0
	s_add_u32 s17, s3, s14
	s_mul_i32 s17, s17, 0x800
	s_add_u32 s8, s20, s17
	s_addc_u32 s9, s21, 0
	v_mov_b32_e32 v176, v177
	s_mov_b32 s16, 1
	s_waitcnt lgkmcnt(0)
	v_mfma_f32_16x16x32_bf16 v[2:5], v[90:93], v[106:109], v[2:5]
	ds_read_b128 v[144:147], v142 offset:1024
	v_mfma_f32_16x16x32_bf16 v[6:9], v[94:97], v[106:109], v[6:9]
	ds_read_b128 v[148:151], v142 offset:3072
	v_mfma_f32_16x16x32_bf16 v[10:13], v[98:101], v[106:109], v[10:13]
	ds_read_b128 v[152:155], v142 offset:5120
	v_mfma_f32_16x16x32_bf16 v[14:17], v[102:105], v[106:109], v[14:17]
	ds_read_b128 v[156:159], v142 offset:7168
	v_mfma_f32_16x16x32_bf16 v[18:21], v[90:93], v[110:113], v[18:21]
	ds_read_b128 v[160:163], v141 offset:1024
	v_mfma_f32_16x16x32_bf16 v[22:25], v[94:97], v[110:113], v[22:25]
	ds_read_b128 v[164:167], v141 offset:3072
	v_mfma_f32_16x16x32_bf16 v[26:29], v[98:101], v[110:113], v[26:29]
	ds_read_b128 v[168:171], v141 offset:5120
	v_mfma_f32_16x16x32_bf16 v[30:33], v[102:105], v[110:113], v[30:33]
	ds_read_b128 v[172:175], v141 offset:7168
	v_mfma_f32_16x16x32_bf16 v[34:37], v[90:93], v[114:117], v[34:37]
	v_mfma_f32_16x16x32_bf16 v[38:41], v[94:97], v[114:117], v[38:41]
	v_mfma_f32_16x16x32_bf16 v[42:45], v[98:101], v[114:117], v[42:45]
	v_mfma_f32_16x16x32_bf16 v[46:49], v[102:105], v[114:117], v[46:49]
	v_mfma_f32_16x16x32_bf16 v[50:53], v[90:93], v[118:121], v[50:53]
	v_mfma_f32_16x16x32_bf16 v[54:57], v[94:97], v[118:121], v[54:57]
	v_mfma_f32_16x16x32_bf16 v[58:61], v[98:101], v[118:121], v[58:61]
	v_mfma_f32_16x16x32_bf16 v[62:65], v[102:105], v[118:121], v[62:65]
	s_waitcnt vmcnt(0) lgkmcnt(0)
	s_barrier
	v_mfma_f32_16x16x32_bf16 v[2:5], v[144:147], v[160:163], v[2:5]
	ds_read_b128 v[90:93], v142 offset:32768
	s_add_u32 m0, s22, 0x0
	v_mov_b32_e32 v179, v176
	global_load_lds_dwordx4 v179, s[6:7]
	v_mfma_f32_16x16x32_bf16 v[6:9], v[148:151], v[160:163], v[6:9]
	ds_read_b128 v[94:97], v142 offset:34816
	s_add_u32 m0, s22, 0x400
	v_add_u32_e32 v180, 0x40, v176
	global_load_lds_dwordx4 v180, s[6:7]
	v_mfma_f32_16x16x32_bf16 v[10:13], v[152:155], v[160:163], v[10:13]
	ds_read_b128 v[98:101], v142 offset:36864
	s_add_u32 m0, s22, 0x800
	v_add_u32_e32 v179, 0x8000, v176
	global_load_lds_dwordx4 v179, s[6:7]
	v_mfma_f32_16x16x32_bf16 v[14:17], v[156:159], v[160:163], v[14:17]
	ds_read_b128 v[102:105], v142 offset:38912
	s_add_u32 m0, s22, 0xc00
	v_add_u32_e32 v180, 0x8040, v176
	global_load_lds_dwordx4 v180, s[6:7]
	v_mfma_f32_16x16x32_bf16 v[18:21], v[144:147], v[164:167], v[18:21]
	ds_read_b128 v[106:109], v141 offset:32768
	s_add_u32 m0, s22, 0x4000
	v_mov_b32_e32 v179, v176
	global_load_lds_dwordx4 v179, s[8:9]
	v_mfma_f32_16x16x32_bf16 v[22:25], v[148:151], v[164:167], v[22:25]
	ds_read_b128 v[110:113], v141 offset:34816
	s_add_u32 m0, s22, 0x4400
	v_add_u32_e32 v180, 0x40, v176
	global_load_lds_dwordx4 v180, s[8:9]
	v_mfma_f32_16x16x32_bf16 v[26:29], v[152:155], v[164:167], v[26:29]
	ds_read_b128 v[114:117], v141 offset:36864
	s_add_u32 m0, s22, 0x4800
	v_add_u32_e32 v179, 0x8000, v176
	global_load_lds_dwordx4 v179, s[8:9]
	v_mfma_f32_16x16x32_bf16 v[30:33], v[156:159], v[164:167], v[30:33]
	ds_read_b128 v[118:121], v141 offset:38912
	s_add_u32 m0, s22, 0x4c00
	v_add_u32_e32 v180, 0x8040, v176
	global_load_lds_dwordx4 v180, s[8:9]
	v_mfma_f32_16x16x32_bf16 v[34:37], v[144:147], v[168:171], v[34:37]
	v_mfma_f32_16x16x32_bf16 v[38:41], v[148:151], v[168:171], v[38:41]
	v_mfma_f32_16x16x32_bf16 v[42:45], v[152:155], v[168:171], v[42:45]
	v_mfma_f32_16x16x32_bf16 v[46:49], v[156:159], v[168:171], v[46:49]
	v_mfma_f32_16x16x32_bf16 v[50:53], v[144:147], v[172:175], v[50:53]
	v_mfma_f32_16x16x32_bf16 v[54:57], v[148:151], v[172:175], v[54:57]
	v_mfma_f32_16x16x32_bf16 v[58:61], v[152:155], v[172:175], v[58:61]
	v_mfma_f32_16x16x32_bf16 v[62:65], v[156:159], v[172:175], v[62:65]
	v_add_u32_e32 v176, 0x80, v176
	s_waitcnt lgkmcnt(0)
	v_mfma_f32_16x16x32_bf16 v[2:5], v[90:93], v[106:109], v[2:5]
	ds_read_b128 v[144:147], v142 offset:33792
	v_mfma_f32_16x16x32_bf16 v[6:9], v[94:97], v[106:109], v[6:9]
	ds_read_b128 v[148:151], v142 offset:35840
	v_mfma_f32_16x16x32_bf16 v[10:13], v[98:101], v[106:109], v[10:13]
	ds_read_b128 v[152:155], v142 offset:37888
	v_mfma_f32_16x16x32_bf16 v[14:17], v[102:105], v[106:109], v[14:17]
	ds_read_b128 v[156:159], v142 offset:39936
	v_mfma_f32_16x16x32_bf16 v[18:21], v[90:93], v[110:113], v[18:21]
	ds_read_b128 v[160:163], v141 offset:33792
	v_mfma_f32_16x16x32_bf16 v[22:25], v[94:97], v[110:113], v[22:25]
	ds_read_b128 v[164:167], v141 offset:35840
	v_mfma_f32_16x16x32_bf16 v[26:29], v[98:101], v[110:113], v[26:29]
	ds_read_b128 v[168:171], v141 offset:37888
	v_mfma_f32_16x16x32_bf16 v[30:33], v[102:105], v[110:113], v[30:33]
	ds_read_b128 v[172:175], v141 offset:39936
	v_mfma_f32_16x16x32_bf16 v[34:37], v[90:93], v[114:117], v[34:37]
	v_mfma_f32_16x16x32_bf16 v[38:41], v[94:97], v[114:117], v[38:41]
	v_mfma_f32_16x16x32_bf16 v[42:45], v[98:101], v[114:117], v[42:45]
	v_mfma_f32_16x16x32_bf16 v[46:49], v[102:105], v[114:117], v[46:49]
	v_mfma_f32_16x16x32_bf16 v[50:53], v[90:93], v[118:121], v[50:53]
	v_mfma_f32_16x16x32_bf16 v[54:57], v[94:97], v[118:121], v[54:57]
	v_mfma_f32_16x16x32_bf16 v[58:61], v[98:101], v[118:121], v[58:61]
	v_mfma_f32_16x16x32_bf16 v[62:65], v[102:105], v[118:121], v[62:65]
	s_waitcnt vmcnt(0) lgkmcnt(0)
	s_barrier
	v_mfma_f32_16x16x32_bf16 v[2:5], v[144:147], v[160:163], v[2:5]
	ds_read_b128 v[90:93], v142
	s_add_u32 m0, s22, 0x8000
	v_mov_b32_e32 v179, v176
	global_load_lds_dwordx4 v179, s[6:7]
	v_mfma_f32_16x16x32_bf16 v[6:9], v[148:151], v[160:163], v[6:9]
	ds_read_b128 v[94:97], v142 offset:2048
	s_add_u32 m0, s22, 0x8400
	v_add_u32_e32 v180, 0x40, v176
	global_load_lds_dwordx4 v180, s[6:7]
	v_mfma_f32_16x16x32_bf16 v[10:13], v[152:155], v[160:163], v[10:13]
	ds_read_b128 v[98:101], v142 offset:4096
	s_add_u32 m0, s22, 0x8800
	v_add_u32_e32 v179, 0x8000, v176
	global_load_lds_dwordx4 v179, s[6:7]
	v_mfma_f32_16x16x32_bf16 v[14:17], v[156:159], v[160:163], v[14:17]
	ds_read_b128 v[102:105], v142 offset:6144
	s_add_u32 m0, s22, 0x8c00
	v_add_u32_e32 v180, 0x8040, v176
	global_load_lds_dwordx4 v180, s[6:7]
	v_mfma_f32_16x16x32_bf16 v[18:21], v[144:147], v[164:167], v[18:21]
	ds_read_b128 v[106:109], v141
	s_add_u32 m0, s22, 0xc000
	v_mov_b32_e32 v179, v176
	global_load_lds_dwordx4 v179, s[8:9]
	v_mfma_f32_16x16x32_bf16 v[22:25], v[148:151], v[164:167], v[22:25]
	ds_read_b128 v[110:113], v141 offset:2048
	s_add_u32 m0, s22, 0xc400
	v_add_u32_e32 v180, 0x40, v176
	global_load_lds_dwordx4 v180, s[8:9]
	v_mfma_f32_16x16x32_bf16 v[26:29], v[152:155], v[164:167], v[26:29]
	ds_read_b128 v[114:117], v141 offset:4096
	s_add_u32 m0, s22, 0xc800
	v_add_u32_e32 v179, 0x8000, v176
	global_load_lds_dwordx4 v179, s[8:9]
	v_mfma_f32_16x16x32_bf16 v[30:33], v[156:159], v[164:167], v[30:33]
	ds_read_b128 v[118:121], v141 offset:6144
	s_add_u32 m0, s22, 0xcc00
	v_add_u32_e32 v180, 0x8040, v176
	global_load_lds_dwordx4 v180, s[8:9]
	v_mfma_f32_16x16x32_bf16 v[34:37], v[144:147], v[168:171], v[34:37]
	global_load_dwordx4 v[196:199], v181, s[4:5]
	v_mfma_f32_16x16x32_bf16 v[38:41], v[148:151], v[168:171], v[38:41]
	global_load_dwordx4 v[200:203], v181, s[4:5] offset:64
	global_load_dwordx4 v[204:207], v181, s[4:5] offset:128
	v_mfma_f32_16x16x32_bf16 v[42:45], v[152:155], v[168:171], v[42:45]
	global_load_dwordx4 v[212:215], v181, s[4:5] offset:192
	v_mfma_f32_16x16x32_bf16 v[46:49], v[156:159], v[168:171], v[46:49]
	global_load_dwordx4 v[66:69], v178, s[26:27]
	global_load_dwordx4 v[70:73], v178, s[26:27] offset:64
	v_mfma_f32_16x16x32_bf16 v[50:53], v[144:147], v[172:175], v[50:53]
	global_load_dwordx4 v[74:77], v178, s[26:27] offset:128
	v_mfma_f32_16x16x32_bf16 v[54:57], v[148:151], v[172:175], v[54:57]
	global_load_dwordx4 v[78:81], v178, s[26:27] offset:192
	v_add_u32_e32 v216, 0x10000, v178
	global_load_dwordx4 v[82:85], v216, s[26:27]
	v_mfma_f32_16x16x32_bf16 v[58:61], v[152:155], v[172:175], v[58:61]
	global_load_dwordx4 v[86:89], v216, s[26:27] offset:64
	v_mfma_f32_16x16x32_bf16 v[62:65], v[156:159], v[172:175], v[62:65]
	global_load_dwordx4 v[122:125], v216, s[26:27] offset:128
	global_load_dwordx4 v[126:129], v216, s[26:27] offset:192
	v_add_u32_e32 v176, 0x80, v176
	s_branch .Lg128_wo_epi
